# scan step: mLSTM n-state serial loop (64 x load->wait->store on two workgroups) replaced by hand-written version with all loads hoisted and gate scalars broadcast by v_readlane
# speedup vs baseline: 1.0036x; 1.0023x over previous
; __device__ __forceinline__ void scan_phase(unsigned char* ws, int T0, int TS, bf16* dummy_out = nullptr) {
;     ...
;     if (!dummy_out) for (int T = T0; T < 1024; T += TS) {
;         const int head = T >> 8, d = T & 255; float* np = (float*)(ws + WS_NST) + (size_t)head * NPAIR * 256 + d; float n = 0.f, mrun = 0.f;
; #pragma unroll 1
;         for (int p = 0; p < NPAIR; ++p) { const float x = np[p * 256]; np[p * 256] = n;
.LBB0_467:
	v_ashrrev_i32_e32 v4, 8, v85
	v_ashrrev_i32_e32 v5, 31, v4
	v_lshlrev_b64 v[6:7], 16, v[4:5]
	v_lshlrev_b32_e32 v4, 7, v4
	v_ashrrev_i32_e32 v5, 31, v4
	v_lshl_add_u64 v[4:5], v[4:5], 2, s[10:11]
	v_lshl_add_u64 v[6:7], v[2:3], 0, v[6:7]
	s_mov_b32 s15, 64
	v_mov_b32_e32 v8, 0
	v_mov_b32_e32 v9, v1
	v_lshl_add_u64 v[16:17], v[6:7], 0, s[8:9]
	v_mov_b32_e32 v18, v16
	v_mov_b32_e32 v19, v17
	s_mov_b32 s44, 0x1000
	s_mov_b32 s45, 0
	v_mbcnt_lo_u32_b32 v168, -1, 0
	v_mbcnt_hi_u32_b32 v168, -1, v168
	v_lshlrev_b32_e32 v168, 3, v168
	v_mov_b32_e32 v169, 0
	v_lshl_add_u64 v[170:171], v[4:5], 0, s[8:9]
	v_lshl_add_u64 v[170:171], v[170:171], 0, v[168:169]
	v_add_co_u32_e32 v170, vcc, 0x260000, v170
	s_nop 1
	v_addc_co_u32_e32 v171, vcc, 0, v171, vcc
	global_load_dwordx2 v[164:165], v[170:171], off
	global_load_dwordx2 v[166:167], v[170:171], off offset:2048
	global_load_dword v100, v[16:17], off
	global_load_dword v101, v[16:17], off offset:1024
	global_load_dword v102, v[16:17], off offset:2048
	global_load_dword v103, v[16:17], off offset:3072
	v_lshl_add_u64 v[16:17], v[16:17], 0, s[44:45]
	global_load_dword v104, v[16:17], off
	global_load_dword v105, v[16:17], off offset:1024
	global_load_dword v106, v[16:17], off offset:2048
	global_load_dword v107, v[16:17], off offset:3072
	v_lshl_add_u64 v[16:17], v[16:17], 0, s[44:45]
	global_load_dword v108, v[16:17], off
	global_load_dword v109, v[16:17], off offset:1024
	global_load_dword v110, v[16:17], off offset:2048
	global_load_dword v111, v[16:17], off offset:3072
	v_lshl_add_u64 v[16:17], v[16:17], 0, s[44:45]
	global_load_dword v112, v[16:17], off
	global_load_dword v113, v[16:17], off offset:1024
	global_load_dword v114, v[16:17], off offset:2048
	global_load_dword v115, v[16:17], off offset:3072
	v_lshl_add_u64 v[16:17], v[16:17], 0, s[44:45]
	global_load_dword v116, v[16:17], off
	global_load_dword v117, v[16:17], off offset:1024
	global_load_dword v118, v[16:17], off offset:2048
	global_load_dword v119, v[16:17], off offset:3072
	v_lshl_add_u64 v[16:17], v[16:17], 0, s[44:45]
	global_load_dword v120, v[16:17], off
	global_load_dword v121, v[16:17], off offset:1024
	global_load_dword v122, v[16:17], off offset:2048
	global_load_dword v123, v[16:17], off offset:3072
	v_lshl_add_u64 v[16:17], v[16:17], 0, s[44:45]
	global_load_dword v124, v[16:17], off
	global_load_dword v125, v[16:17], off offset:1024
	global_load_dword v126, v[16:17], off offset:2048
	global_load_dword v127, v[16:17], off offset:3072
	v_lshl_add_u64 v[16:17], v[16:17], 0, s[44:45]
	global_load_dword v128, v[16:17], off
	global_load_dword v129, v[16:17], off offset:1024
	global_load_dword v130, v[16:17], off offset:2048
	global_load_dword v131, v[16:17], off offset:3072
	v_lshl_add_u64 v[16:17], v[16:17], 0, s[44:45]
	global_load_dword v132, v[16:17], off
	global_load_dword v133, v[16:17], off offset:1024
	global_load_dword v134, v[16:17], off offset:2048
	global_load_dword v135, v[16:17], off offset:3072
	v_lshl_add_u64 v[16:17], v[16:17], 0, s[44:45]
	global_load_dword v136, v[16:17], off
	global_load_dword v137, v[16:17], off offset:1024
	global_load_dword v138, v[16:17], off offset:2048
	global_load_dword v139, v[16:17], off offset:3072
	v_lshl_add_u64 v[16:17], v[16:17], 0, s[44:45]
	global_load_dword v140, v[16:17], off
	global_load_dword v141, v[16:17], off offset:1024
	global_load_dword v142, v[16:17], off offset:2048
	global_load_dword v143, v[16:17], off offset:3072
	v_lshl_add_u64 v[16:17], v[16:17], 0, s[44:45]
	global_load_dword v144, v[16:17], off
	global_load_dword v145, v[16:17], off offset:1024
	global_load_dword v146, v[16:17], off offset:2048
	global_load_dword v147, v[16:17], off offset:3072
	v_lshl_add_u64 v[16:17], v[16:17], 0, s[44:45]
	global_load_dword v148, v[16:17], off
	global_load_dword v149, v[16:17], off offset:1024
	global_load_dword v150, v[16:17], off offset:2048
	global_load_dword v151, v[16:17], off offset:3072
	v_lshl_add_u64 v[16:17], v[16:17], 0, s[44:45]
	global_load_dword v152, v[16:17], off
	global_load_dword v153, v[16:17], off offset:1024
	global_load_dword v154, v[16:17], off offset:2048
	global_load_dword v155, v[16:17], off offset:3072
	v_lshl_add_u64 v[16:17], v[16:17], 0, s[44:45]
	global_load_dword v156, v[16:17], off
	global_load_dword v157, v[16:17], off offset:1024
	global_load_dword v158, v[16:17], off offset:2048
	global_load_dword v159, v[16:17], off offset:3072
	v_lshl_add_u64 v[16:17], v[16:17], 0, s[44:45]
	global_load_dword v160, v[16:17], off
	global_load_dword v161, v[16:17], off offset:1024
	global_load_dword v162, v[16:17], off offset:2048
	global_load_dword v163, v[16:17], off offset:3072
	s_waitcnt vmcnt(0)
; __device__ __forceinline__ float fexpf(float x) { return __builtin_amdgcn_exp2f(1.4426950408889634f * x); }
; __device__ __forceinline__ void scan_phase(unsigned char* ws, int T0, int TS, bf16* dummy_out = nullptr) {
;     ...
;         for (int p = 0; p < NPAIR; ++p) { const float x = np[p * 256]; np[p * 256] = n;
;             const float blA = mls[MLS_CHB + head * NCH + 2 * p], blB = mls[MLS_CHB + head * NCH + 2 * p + 1];
;             const float pmP = fmaxf(mls[MLS_CHP + head * NCH + 2 * p], mls[MLS_CHP + head * NCH + 2 * p + 1] - blA), m63 = fmaxf(pmP, mrun);
;             n = fexpf(mrun - m63) * n + fexpf(pmP - m63) * x; mrun = (blA + blB) + m63; }
	v_readlane_b32 s20, v164, 0
	v_readlane_b32 s21, v165, 0
	v_readlane_b32 s22, v166, 0
	v_readlane_b32 s23, v167, 0
	v_readlane_b32 s24, v164, 1
	v_readlane_b32 s25, v165, 1
	v_readlane_b32 s26, v166, 1
	v_readlane_b32 s27, v167, 1
	v_mov_b32_e32 v12, s20
	v_mov_b32_e32 v13, s21
	v_mov_b32_e32 v14, s22
	v_mov_b32_e32 v15, s23
	global_store_dword v[18:19], v9, off
	v_max_f32_e32 v10, v8, v8
	v_sub_f32_e32 v11, v15, v12
	v_max_f32_e32 v14, v14, v14
	v_max_f32_e32 v11, v14, v11
	v_max_f32_e32 v10, v11, v10
	v_sub_f32_e32 v8, v8, v10
	v_sub_f32_e32 v11, v11, v10
	v_mul_f32_e32 v8, 0x3fb8aa3b, v8
	v_mul_f32_e32 v11, 0x3fb8aa3b, v11
	v_exp_f32_e32 v8, v8
	v_exp_f32_e32 v11, v11
	v_pk_add_f32 v[12:13], v[12:13], v[12:13] op_sel:[0,1] op_sel_hi:[1,0]
	v_mul_f32_e32 v11, v100, v11
	v_mul_f32_e32 v13, v9, v8
	v_pk_add_f32 v[8:9], v[12:13], v[10:11]
	v_readlane_b32 s20, v164, 2
	v_readlane_b32 s21, v165, 2
	v_readlane_b32 s22, v166, 2
	v_readlane_b32 s23, v167, 2
	v_mov_b32_e32 v12, s24
	v_mov_b32_e32 v13, s25
	v_mov_b32_e32 v14, s26
	v_mov_b32_e32 v15, s27
	global_store_dword v[18:19], v9, off offset:1024
	v_max_f32_e32 v10, v8, v8
	v_sub_f32_e32 v11, v15, v12
	v_max_f32_e32 v14, v14, v14
	v_max_f32_e32 v11, v14, v11
	v_max_f32_e32 v10, v11, v10
	v_sub_f32_e32 v8, v8, v10
	v_sub_f32_e32 v11, v11, v10
	v_mul_f32_e32 v8, 0x3fb8aa3b, v8
	v_mul_f32_e32 v11, 0x3fb8aa3b, v11
	v_exp_f32_e32 v8, v8
	v_exp_f32_e32 v11, v11
	v_pk_add_f32 v[12:13], v[12:13], v[12:13] op_sel:[0,1] op_sel_hi:[1,0]
	v_mul_f32_e32 v11, v101, v11
	v_mul_f32_e32 v13, v9, v8
	v_pk_add_f32 v[8:9], v[12:13], v[10:11]
	v_readlane_b32 s24, v164, 3
	v_readlane_b32 s25, v165, 3
	v_readlane_b32 s26, v166, 3
	v_readlane_b32 s27, v167, 3
	v_mov_b32_e32 v12, s20
	v_mov_b32_e32 v13, s21
	v_mov_b32_e32 v14, s22
	v_mov_b32_e32 v15, s23
	global_store_dword v[18:19], v9, off offset:2048
	v_max_f32_e32 v10, v8, v8
	v_sub_f32_e32 v11, v15, v12
	v_max_f32_e32 v14, v14, v14
	v_max_f32_e32 v11, v14, v11
	v_max_f32_e32 v10, v11, v10
	v_sub_f32_e32 v8, v8, v10
	v_sub_f32_e32 v11, v11, v10
	v_mul_f32_e32 v8, 0x3fb8aa3b, v8
	v_mul_f32_e32 v11, 0x3fb8aa3b, v11
	v_exp_f32_e32 v8, v8
	v_exp_f32_e32 v11, v11
	v_pk_add_f32 v[12:13], v[12:13], v[12:13] op_sel:[0,1] op_sel_hi:[1,0]
	v_mul_f32_e32 v11, v102, v11
	v_mul_f32_e32 v13, v9, v8
	v_pk_add_f32 v[8:9], v[12:13], v[10:11]
	v_readlane_b32 s20, v164, 4
	v_readlane_b32 s21, v165, 4
	v_readlane_b32 s22, v166, 4
	v_readlane_b32 s23, v167, 4
	v_mov_b32_e32 v12, s24
	v_mov_b32_e32 v13, s25
	v_mov_b32_e32 v14, s26
	v_mov_b32_e32 v15, s27
	global_store_dword v[18:19], v9, off offset:3072
	v_lshl_add_u64 v[18:19], v[18:19], 0, s[44:45]
	v_max_f32_e32 v10, v8, v8
	v_sub_f32_e32 v11, v15, v12
	v_max_f32_e32 v14, v14, v14
	v_max_f32_e32 v11, v14, v11
	v_max_f32_e32 v10, v11, v10
	v_sub_f32_e32 v8, v8, v10
	v_sub_f32_e32 v11, v11, v10
	v_mul_f32_e32 v8, 0x3fb8aa3b, v8
	v_mul_f32_e32 v11, 0x3fb8aa3b, v11
	v_exp_f32_e32 v8, v8
	v_exp_f32_e32 v11, v11
	v_pk_add_f32 v[12:13], v[12:13], v[12:13] op_sel:[0,1] op_sel_hi:[1,0]
	v_mul_f32_e32 v11, v103, v11
	v_mul_f32_e32 v13, v9, v8
	v_pk_add_f32 v[8:9], v[12:13], v[10:11]
	v_readlane_b32 s24, v164, 5
	v_readlane_b32 s25, v165, 5
	v_readlane_b32 s26, v166, 5
	v_readlane_b32 s27, v167, 5
	v_mov_b32_e32 v12, s20
	v_mov_b32_e32 v13, s21
	v_mov_b32_e32 v14, s22
	v_mov_b32_e32 v15, s23
	global_store_dword v[18:19], v9, off
	v_max_f32_e32 v10, v8, v8
	v_sub_f32_e32 v11, v15, v12
	v_max_f32_e32 v14, v14, v14
	v_max_f32_e32 v11, v14, v11
	v_max_f32_e32 v10, v11, v10
	v_sub_f32_e32 v8, v8, v10
	v_sub_f32_e32 v11, v11, v10
	v_mul_f32_e32 v8, 0x3fb8aa3b, v8
	v_mul_f32_e32 v11, 0x3fb8aa3b, v11
	v_exp_f32_e32 v8, v8
	v_exp_f32_e32 v11, v11
	v_pk_add_f32 v[12:13], v[12:13], v[12:13] op_sel:[0,1] op_sel_hi:[1,0]
	v_mul_f32_e32 v11, v104, v11
	v_mul_f32_e32 v13, v9, v8
	v_pk_add_f32 v[8:9], v[12:13], v[10:11]
	v_readlane_b32 s20, v164, 6
	v_readlane_b32 s21, v165, 6
	v_readlane_b32 s22, v166, 6
	v_readlane_b32 s23, v167, 6
	v_mov_b32_e32 v12, s24
	v_mov_b32_e32 v13, s25
	v_mov_b32_e32 v14, s26
	v_mov_b32_e32 v15, s27
	global_store_dword v[18:19], v9, off offset:1024
	v_max_f32_e32 v10, v8, v8
	v_sub_f32_e32 v11, v15, v12
	v_max_f32_e32 v14, v14, v14
	v_max_f32_e32 v11, v14, v11
	v_max_f32_e32 v10, v11, v10
	v_sub_f32_e32 v8, v8, v10
	v_sub_f32_e32 v11, v11, v10
	v_mul_f32_e32 v8, 0x3fb8aa3b, v8
	v_mul_f32_e32 v11, 0x3fb8aa3b, v11
	v_exp_f32_e32 v8, v8
	v_exp_f32_e32 v11, v11
	v_pk_add_f32 v[12:13], v[12:13], v[12:13] op_sel:[0,1] op_sel_hi:[1,0]
	v_mul_f32_e32 v11, v105, v11
	v_mul_f32_e32 v13, v9, v8
	v_pk_add_f32 v[8:9], v[12:13], v[10:11]
	v_readlane_b32 s24, v164, 7
	v_readlane_b32 s25, v165, 7
	v_readlane_b32 s26, v166, 7
	v_readlane_b32 s27, v167, 7
	v_mov_b32_e32 v12, s20
	v_mov_b32_e32 v13, s21
	v_mov_b32_e32 v14, s22
	v_mov_b32_e32 v15, s23
	global_store_dword v[18:19], v9, off offset:2048
	v_max_f32_e32 v10, v8, v8
	v_sub_f32_e32 v11, v15, v12
	v_max_f32_e32 v14, v14, v14
	v_max_f32_e32 v11, v14, v11
	v_max_f32_e32 v10, v11, v10
	v_sub_f32_e32 v8, v8, v10
	v_sub_f32_e32 v11, v11, v10
	v_mul_f32_e32 v8, 0x3fb8aa3b, v8
	v_mul_f32_e32 v11, 0x3fb8aa3b, v11
	v_exp_f32_e32 v8, v8
	v_exp_f32_e32 v11, v11
	v_pk_add_f32 v[12:13], v[12:13], v[12:13] op_sel:[0,1] op_sel_hi:[1,0]
	v_mul_f32_e32 v11, v106, v11
	v_mul_f32_e32 v13, v9, v8
	v_pk_add_f32 v[8:9], v[12:13], v[10:11]
	v_readlane_b32 s20, v164, 8
	v_readlane_b32 s21, v165, 8
	v_readlane_b32 s22, v166, 8
	v_readlane_b32 s23, v167, 8
	v_mov_b32_e32 v12, s24
	v_mov_b32_e32 v13, s25
	v_mov_b32_e32 v14, s26
	v_mov_b32_e32 v15, s27
	global_store_dword v[18:19], v9, off offset:3072
; __device__ __forceinline__ float fexpf(float x) { return __builtin_amdgcn_exp2f(1.4426950408889634f * x); }
; __device__ __forceinline__ void scan_phase(unsigned char* ws, int T0, int TS, bf16* dummy_out = nullptr) {
;     ...
;         for (int p = 0; p < NPAIR; ++p) { const float x = np[p * 256]; np[p * 256] = n;
;             const float blA = mls[MLS_CHB + head * NCH + 2 * p], blB = mls[MLS_CHB + head * NCH + 2 * p + 1];
;             const float pmP = fmaxf(mls[MLS_CHP + head * NCH + 2 * p], mls[MLS_CHP + head * NCH + 2 * p + 1] - blA), m63 = fmaxf(pmP, mrun);
;             n = fexpf(mrun - m63) * n + fexpf(pmP - m63) * x; mrun = (blA + blB) + m63; }
	v_lshl_add_u64 v[18:19], v[18:19], 0, s[44:45]
	v_max_f32_e32 v10, v8, v8
	v_sub_f32_e32 v11, v15, v12
	v_max_f32_e32 v14, v14, v14
	v_max_f32_e32 v11, v14, v11
	v_max_f32_e32 v10, v11, v10
	v_sub_f32_e32 v8, v8, v10
	v_sub_f32_e32 v11, v11, v10
	v_mul_f32_e32 v8, 0x3fb8aa3b, v8
	v_mul_f32_e32 v11, 0x3fb8aa3b, v11
	v_exp_f32_e32 v8, v8
	v_exp_f32_e32 v11, v11
	v_pk_add_f32 v[12:13], v[12:13], v[12:13] op_sel:[0,1] op_sel_hi:[1,0]
	v_mul_f32_e32 v11, v107, v11
	v_mul_f32_e32 v13, v9, v8
	v_pk_add_f32 v[8:9], v[12:13], v[10:11]
	v_readlane_b32 s24, v164, 9
	v_readlane_b32 s25, v165, 9
	v_readlane_b32 s26, v166, 9
	v_readlane_b32 s27, v167, 9
	v_mov_b32_e32 v12, s20
	v_mov_b32_e32 v13, s21
	v_mov_b32_e32 v14, s22
	v_mov_b32_e32 v15, s23
	global_store_dword v[18:19], v9, off
	v_max_f32_e32 v10, v8, v8
	v_sub_f32_e32 v11, v15, v12
	v_max_f32_e32 v14, v14, v14
	v_max_f32_e32 v11, v14, v11
	v_max_f32_e32 v10, v11, v10
	v_sub_f32_e32 v8, v8, v10
	v_sub_f32_e32 v11, v11, v10
	v_mul_f32_e32 v8, 0x3fb8aa3b, v8
	v_mul_f32_e32 v11, 0x3fb8aa3b, v11
	v_exp_f32_e32 v8, v8
	v_exp_f32_e32 v11, v11
	v_pk_add_f32 v[12:13], v[12:13], v[12:13] op_sel:[0,1] op_sel_hi:[1,0]
	v_mul_f32_e32 v11, v108, v11
	v_mul_f32_e32 v13, v9, v8
	v_pk_add_f32 v[8:9], v[12:13], v[10:11]
	v_readlane_b32 s20, v164, 10
	v_readlane_b32 s21, v165, 10
	v_readlane_b32 s22, v166, 10
	v_readlane_b32 s23, v167, 10
	v_mov_b32_e32 v12, s24
	v_mov_b32_e32 v13, s25
	v_mov_b32_e32 v14, s26
	v_mov_b32_e32 v15, s27
	global_store_dword v[18:19], v9, off offset:1024
	v_max_f32_e32 v10, v8, v8
	v_sub_f32_e32 v11, v15, v12
	v_max_f32_e32 v14, v14, v14
	v_max_f32_e32 v11, v14, v11
	v_max_f32_e32 v10, v11, v10
	v_sub_f32_e32 v8, v8, v10
	v_sub_f32_e32 v11, v11, v10
	v_mul_f32_e32 v8, 0x3fb8aa3b, v8
	v_mul_f32_e32 v11, 0x3fb8aa3b, v11
	v_exp_f32_e32 v8, v8
	v_exp_f32_e32 v11, v11
	v_pk_add_f32 v[12:13], v[12:13], v[12:13] op_sel:[0,1] op_sel_hi:[1,0]
	v_mul_f32_e32 v11, v109, v11
	v_mul_f32_e32 v13, v9, v8
	v_pk_add_f32 v[8:9], v[12:13], v[10:11]
	v_readlane_b32 s24, v164, 11
	v_readlane_b32 s25, v165, 11
	v_readlane_b32 s26, v166, 11
	v_readlane_b32 s27, v167, 11
	v_mov_b32_e32 v12, s20
	v_mov_b32_e32 v13, s21
	v_mov_b32_e32 v14, s22
	v_mov_b32_e32 v15, s23
	global_store_dword v[18:19], v9, off offset:2048
	v_max_f32_e32 v10, v8, v8
	v_sub_f32_e32 v11, v15, v12
	v_max_f32_e32 v14, v14, v14
	v_max_f32_e32 v11, v14, v11
	v_max_f32_e32 v10, v11, v10
	v_sub_f32_e32 v8, v8, v10
	v_sub_f32_e32 v11, v11, v10
	v_mul_f32_e32 v8, 0x3fb8aa3b, v8
	v_mul_f32_e32 v11, 0x3fb8aa3b, v11
	v_exp_f32_e32 v8, v8
	v_exp_f32_e32 v11, v11
	v_pk_add_f32 v[12:13], v[12:13], v[12:13] op_sel:[0,1] op_sel_hi:[1,0]
	v_mul_f32_e32 v11, v110, v11
	v_mul_f32_e32 v13, v9, v8
	v_pk_add_f32 v[8:9], v[12:13], v[10:11]
	v_readlane_b32 s20, v164, 12
	v_readlane_b32 s21, v165, 12
	v_readlane_b32 s22, v166, 12
	v_readlane_b32 s23, v167, 12
	v_mov_b32_e32 v12, s24
	v_mov_b32_e32 v13, s25
	v_mov_b32_e32 v14, s26
	v_mov_b32_e32 v15, s27
	global_store_dword v[18:19], v9, off offset:3072
	v_lshl_add_u64 v[18:19], v[18:19], 0, s[44:45]
	v_max_f32_e32 v10, v8, v8
	v_sub_f32_e32 v11, v15, v12
	v_max_f32_e32 v14, v14, v14
	v_max_f32_e32 v11, v14, v11
	v_max_f32_e32 v10, v11, v10
	v_sub_f32_e32 v8, v8, v10
	v_sub_f32_e32 v11, v11, v10
	v_mul_f32_e32 v8, 0x3fb8aa3b, v8
	v_mul_f32_e32 v11, 0x3fb8aa3b, v11
	v_exp_f32_e32 v8, v8
	v_exp_f32_e32 v11, v11
	v_pk_add_f32 v[12:13], v[12:13], v[12:13] op_sel:[0,1] op_sel_hi:[1,0]
	v_mul_f32_e32 v11, v111, v11
	v_mul_f32_e32 v13, v9, v8
	v_pk_add_f32 v[8:9], v[12:13], v[10:11]
	v_readlane_b32 s24, v164, 13
	v_readlane_b32 s25, v165, 13
	v_readlane_b32 s26, v166, 13
	v_readlane_b32 s27, v167, 13
	v_mov_b32_e32 v12, s20
	v_mov_b32_e32 v13, s21
	v_mov_b32_e32 v14, s22
	v_mov_b32_e32 v15, s23
	global_store_dword v[18:19], v9, off
	v_max_f32_e32 v10, v8, v8
	v_sub_f32_e32 v11, v15, v12
	v_max_f32_e32 v14, v14, v14
	v_max_f32_e32 v11, v14, v11
	v_max_f32_e32 v10, v11, v10
	v_sub_f32_e32 v8, v8, v10
	v_sub_f32_e32 v11, v11, v10
	v_mul_f32_e32 v8, 0x3fb8aa3b, v8
	v_mul_f32_e32 v11, 0x3fb8aa3b, v11
	v_exp_f32_e32 v8, v8
	v_exp_f32_e32 v11, v11
	v_pk_add_f32 v[12:13], v[12:13], v[12:13] op_sel:[0,1] op_sel_hi:[1,0]
	v_mul_f32_e32 v11, v112, v11
	v_mul_f32_e32 v13, v9, v8
	v_pk_add_f32 v[8:9], v[12:13], v[10:11]
	v_readlane_b32 s20, v164, 14
	v_readlane_b32 s21, v165, 14
	v_readlane_b32 s22, v166, 14
	v_readlane_b32 s23, v167, 14
	v_mov_b32_e32 v12, s24
	v_mov_b32_e32 v13, s25
	v_mov_b32_e32 v14, s26
	v_mov_b32_e32 v15, s27
	global_store_dword v[18:19], v9, off offset:1024
	v_max_f32_e32 v10, v8, v8
	v_sub_f32_e32 v11, v15, v12
	v_max_f32_e32 v14, v14, v14
	v_max_f32_e32 v11, v14, v11
	v_max_f32_e32 v10, v11, v10
	v_sub_f32_e32 v8, v8, v10
	v_sub_f32_e32 v11, v11, v10
	v_mul_f32_e32 v8, 0x3fb8aa3b, v8
	v_mul_f32_e32 v11, 0x3fb8aa3b, v11
	v_exp_f32_e32 v8, v8
	v_exp_f32_e32 v11, v11
	v_pk_add_f32 v[12:13], v[12:13], v[12:13] op_sel:[0,1] op_sel_hi:[1,0]
	v_mul_f32_e32 v11, v113, v11
	v_mul_f32_e32 v13, v9, v8
	v_pk_add_f32 v[8:9], v[12:13], v[10:11]
	v_readlane_b32 s24, v164, 15
	v_readlane_b32 s25, v165, 15
	v_readlane_b32 s26, v166, 15
	v_readlane_b32 s27, v167, 15
	v_mov_b32_e32 v12, s20
	v_mov_b32_e32 v13, s21
	v_mov_b32_e32 v14, s22
	v_mov_b32_e32 v15, s23
	global_store_dword v[18:19], v9, off offset:2048
	v_max_f32_e32 v10, v8, v8
	v_sub_f32_e32 v11, v15, v12
	v_max_f32_e32 v14, v14, v14
	v_max_f32_e32 v11, v14, v11
	v_max_f32_e32 v10, v11, v10
	v_sub_f32_e32 v8, v8, v10
	v_sub_f32_e32 v11, v11, v10
	v_mul_f32_e32 v8, 0x3fb8aa3b, v8
	v_mul_f32_e32 v11, 0x3fb8aa3b, v11
	v_exp_f32_e32 v8, v8
	v_exp_f32_e32 v11, v11
; __device__ __forceinline__ float fexpf(float x) { return __builtin_amdgcn_exp2f(1.4426950408889634f * x); }
; __device__ __forceinline__ void scan_phase(unsigned char* ws, int T0, int TS, bf16* dummy_out = nullptr) {
;     ...
;         for (int p = 0; p < NPAIR; ++p) { const float x = np[p * 256]; np[p * 256] = n;
;             const float blA = mls[MLS_CHB + head * NCH + 2 * p], blB = mls[MLS_CHB + head * NCH + 2 * p + 1];
;             const float pmP = fmaxf(mls[MLS_CHP + head * NCH + 2 * p], mls[MLS_CHP + head * NCH + 2 * p + 1] - blA), m63 = fmaxf(pmP, mrun);
;             n = fexpf(mrun - m63) * n + fexpf(pmP - m63) * x; mrun = (blA + blB) + m63; }
	v_pk_add_f32 v[12:13], v[12:13], v[12:13] op_sel:[0,1] op_sel_hi:[1,0]
	v_mul_f32_e32 v11, v114, v11
	v_mul_f32_e32 v13, v9, v8
	v_pk_add_f32 v[8:9], v[12:13], v[10:11]
	v_readlane_b32 s20, v164, 16
	v_readlane_b32 s21, v165, 16
	v_readlane_b32 s22, v166, 16
	v_readlane_b32 s23, v167, 16
	v_mov_b32_e32 v12, s24
	v_mov_b32_e32 v13, s25
	v_mov_b32_e32 v14, s26
	v_mov_b32_e32 v15, s27
	global_store_dword v[18:19], v9, off offset:3072
	v_lshl_add_u64 v[18:19], v[18:19], 0, s[44:45]
	v_max_f32_e32 v10, v8, v8
	v_sub_f32_e32 v11, v15, v12
	v_max_f32_e32 v14, v14, v14
	v_max_f32_e32 v11, v14, v11
	v_max_f32_e32 v10, v11, v10
	v_sub_f32_e32 v8, v8, v10
	v_sub_f32_e32 v11, v11, v10
	v_mul_f32_e32 v8, 0x3fb8aa3b, v8
	v_mul_f32_e32 v11, 0x3fb8aa3b, v11
	v_exp_f32_e32 v8, v8
	v_exp_f32_e32 v11, v11
	v_pk_add_f32 v[12:13], v[12:13], v[12:13] op_sel:[0,1] op_sel_hi:[1,0]
	v_mul_f32_e32 v11, v115, v11
	v_mul_f32_e32 v13, v9, v8
	v_pk_add_f32 v[8:9], v[12:13], v[10:11]
	v_readlane_b32 s24, v164, 17
	v_readlane_b32 s25, v165, 17
	v_readlane_b32 s26, v166, 17
	v_readlane_b32 s27, v167, 17
	v_mov_b32_e32 v12, s20
	v_mov_b32_e32 v13, s21
	v_mov_b32_e32 v14, s22
	v_mov_b32_e32 v15, s23
	global_store_dword v[18:19], v9, off
	v_max_f32_e32 v10, v8, v8
	v_sub_f32_e32 v11, v15, v12
	v_max_f32_e32 v14, v14, v14
	v_max_f32_e32 v11, v14, v11
	v_max_f32_e32 v10, v11, v10
	v_sub_f32_e32 v8, v8, v10
	v_sub_f32_e32 v11, v11, v10
	v_mul_f32_e32 v8, 0x3fb8aa3b, v8
	v_mul_f32_e32 v11, 0x3fb8aa3b, v11
	v_exp_f32_e32 v8, v8
	v_exp_f32_e32 v11, v11
	v_pk_add_f32 v[12:13], v[12:13], v[12:13] op_sel:[0,1] op_sel_hi:[1,0]
	v_mul_f32_e32 v11, v116, v11
	v_mul_f32_e32 v13, v9, v8
	v_pk_add_f32 v[8:9], v[12:13], v[10:11]
	v_readlane_b32 s20, v164, 18
	v_readlane_b32 s21, v165, 18
	v_readlane_b32 s22, v166, 18
	v_readlane_b32 s23, v167, 18
	v_mov_b32_e32 v12, s24
	v_mov_b32_e32 v13, s25
	v_mov_b32_e32 v14, s26
	v_mov_b32_e32 v15, s27
	global_store_dword v[18:19], v9, off offset:1024
	v_max_f32_e32 v10, v8, v8
	v_sub_f32_e32 v11, v15, v12
	v_max_f32_e32 v14, v14, v14
	v_max_f32_e32 v11, v14, v11
	v_max_f32_e32 v10, v11, v10
	v_sub_f32_e32 v8, v8, v10
	v_sub_f32_e32 v11, v11, v10
	v_mul_f32_e32 v8, 0x3fb8aa3b, v8
	v_mul_f32_e32 v11, 0x3fb8aa3b, v11
	v_exp_f32_e32 v8, v8
	v_exp_f32_e32 v11, v11
	v_pk_add_f32 v[12:13], v[12:13], v[12:13] op_sel:[0,1] op_sel_hi:[1,0]
	v_mul_f32_e32 v11, v117, v11
	v_mul_f32_e32 v13, v9, v8
	v_pk_add_f32 v[8:9], v[12:13], v[10:11]
	v_readlane_b32 s24, v164, 19
	v_readlane_b32 s25, v165, 19
	v_readlane_b32 s26, v166, 19
	v_readlane_b32 s27, v167, 19
	v_mov_b32_e32 v12, s20
	v_mov_b32_e32 v13, s21
	v_mov_b32_e32 v14, s22
	v_mov_b32_e32 v15, s23
	global_store_dword v[18:19], v9, off offset:2048
	v_max_f32_e32 v10, v8, v8
	v_sub_f32_e32 v11, v15, v12
	v_max_f32_e32 v14, v14, v14
	v_max_f32_e32 v11, v14, v11
	v_max_f32_e32 v10, v11, v10
	v_sub_f32_e32 v8, v8, v10
	v_sub_f32_e32 v11, v11, v10
	v_mul_f32_e32 v8, 0x3fb8aa3b, v8
	v_mul_f32_e32 v11, 0x3fb8aa3b, v11
	v_exp_f32_e32 v8, v8
	v_exp_f32_e32 v11, v11
	v_pk_add_f32 v[12:13], v[12:13], v[12:13] op_sel:[0,1] op_sel_hi:[1,0]
	v_mul_f32_e32 v11, v118, v11
	v_mul_f32_e32 v13, v9, v8
	v_pk_add_f32 v[8:9], v[12:13], v[10:11]
	v_readlane_b32 s20, v164, 20
	v_readlane_b32 s21, v165, 20
	v_readlane_b32 s22, v166, 20
	v_readlane_b32 s23, v167, 20
	v_mov_b32_e32 v12, s24
	v_mov_b32_e32 v13, s25
	v_mov_b32_e32 v14, s26
	v_mov_b32_e32 v15, s27
	global_store_dword v[18:19], v9, off offset:3072
	v_lshl_add_u64 v[18:19], v[18:19], 0, s[44:45]
	v_max_f32_e32 v10, v8, v8
	v_sub_f32_e32 v11, v15, v12
	v_max_f32_e32 v14, v14, v14
	v_max_f32_e32 v11, v14, v11
	v_max_f32_e32 v10, v11, v10
	v_sub_f32_e32 v8, v8, v10
	v_sub_f32_e32 v11, v11, v10
	v_mul_f32_e32 v8, 0x3fb8aa3b, v8
	v_mul_f32_e32 v11, 0x3fb8aa3b, v11
	v_exp_f32_e32 v8, v8
	v_exp_f32_e32 v11, v11
	v_pk_add_f32 v[12:13], v[12:13], v[12:13] op_sel:[0,1] op_sel_hi:[1,0]
	v_mul_f32_e32 v11, v119, v11
	v_mul_f32_e32 v13, v9, v8
	v_pk_add_f32 v[8:9], v[12:13], v[10:11]
	v_readlane_b32 s24, v164, 21
	v_readlane_b32 s25, v165, 21
	v_readlane_b32 s26, v166, 21
	v_readlane_b32 s27, v167, 21
	v_mov_b32_e32 v12, s20
	v_mov_b32_e32 v13, s21
	v_mov_b32_e32 v14, s22
	v_mov_b32_e32 v15, s23
	global_store_dword v[18:19], v9, off
	v_max_f32_e32 v10, v8, v8
	v_sub_f32_e32 v11, v15, v12
	v_max_f32_e32 v14, v14, v14
	v_max_f32_e32 v11, v14, v11
	v_max_f32_e32 v10, v11, v10
	v_sub_f32_e32 v8, v8, v10
	v_sub_f32_e32 v11, v11, v10
	v_mul_f32_e32 v8, 0x3fb8aa3b, v8
	v_mul_f32_e32 v11, 0x3fb8aa3b, v11
	v_exp_f32_e32 v8, v8
	v_exp_f32_e32 v11, v11
	v_pk_add_f32 v[12:13], v[12:13], v[12:13] op_sel:[0,1] op_sel_hi:[1,0]
	v_mul_f32_e32 v11, v120, v11
	v_mul_f32_e32 v13, v9, v8
	v_pk_add_f32 v[8:9], v[12:13], v[10:11]
	v_readlane_b32 s20, v164, 22
	v_readlane_b32 s21, v165, 22
	v_readlane_b32 s22, v166, 22
	v_readlane_b32 s23, v167, 22
	v_mov_b32_e32 v12, s24
	v_mov_b32_e32 v13, s25
	v_mov_b32_e32 v14, s26
	v_mov_b32_e32 v15, s27
	global_store_dword v[18:19], v9, off offset:1024
	v_max_f32_e32 v10, v8, v8
	v_sub_f32_e32 v11, v15, v12
	v_max_f32_e32 v14, v14, v14
	v_max_f32_e32 v11, v14, v11
	v_max_f32_e32 v10, v11, v10
	v_sub_f32_e32 v8, v8, v10
	v_sub_f32_e32 v11, v11, v10
	v_mul_f32_e32 v8, 0x3fb8aa3b, v8
	v_mul_f32_e32 v11, 0x3fb8aa3b, v11
	v_exp_f32_e32 v8, v8
	v_exp_f32_e32 v11, v11
	v_pk_add_f32 v[12:13], v[12:13], v[12:13] op_sel:[0,1] op_sel_hi:[1,0]
	v_mul_f32_e32 v11, v121, v11
	v_mul_f32_e32 v13, v9, v8
	v_pk_add_f32 v[8:9], v[12:13], v[10:11]
	v_readlane_b32 s24, v164, 23
	v_readlane_b32 s25, v165, 23
	v_readlane_b32 s26, v166, 23
	v_readlane_b32 s27, v167, 23
	v_mov_b32_e32 v12, s20
; __device__ __forceinline__ float fexpf(float x) { return __builtin_amdgcn_exp2f(1.4426950408889634f * x); }
; __device__ __forceinline__ void scan_phase(unsigned char* ws, int T0, int TS, bf16* dummy_out = nullptr) {
;     ...
;         for (int p = 0; p < NPAIR; ++p) { const float x = np[p * 256]; np[p * 256] = n;
;             const float blA = mls[MLS_CHB + head * NCH + 2 * p], blB = mls[MLS_CHB + head * NCH + 2 * p + 1];
;             const float pmP = fmaxf(mls[MLS_CHP + head * NCH + 2 * p], mls[MLS_CHP + head * NCH + 2 * p + 1] - blA), m63 = fmaxf(pmP, mrun);
;             n = fexpf(mrun - m63) * n + fexpf(pmP - m63) * x; mrun = (blA + blB) + m63; }
	v_mov_b32_e32 v13, s21
	v_mov_b32_e32 v14, s22
	v_mov_b32_e32 v15, s23
	global_store_dword v[18:19], v9, off offset:2048
	v_max_f32_e32 v10, v8, v8
	v_sub_f32_e32 v11, v15, v12
	v_max_f32_e32 v14, v14, v14
	v_max_f32_e32 v11, v14, v11
	v_max_f32_e32 v10, v11, v10
	v_sub_f32_e32 v8, v8, v10
	v_sub_f32_e32 v11, v11, v10
	v_mul_f32_e32 v8, 0x3fb8aa3b, v8
	v_mul_f32_e32 v11, 0x3fb8aa3b, v11
	v_exp_f32_e32 v8, v8
	v_exp_f32_e32 v11, v11
	v_pk_add_f32 v[12:13], v[12:13], v[12:13] op_sel:[0,1] op_sel_hi:[1,0]
	v_mul_f32_e32 v11, v122, v11
	v_mul_f32_e32 v13, v9, v8
	v_pk_add_f32 v[8:9], v[12:13], v[10:11]
	v_readlane_b32 s20, v164, 24
	v_readlane_b32 s21, v165, 24
	v_readlane_b32 s22, v166, 24
	v_readlane_b32 s23, v167, 24
	v_mov_b32_e32 v12, s24
	v_mov_b32_e32 v13, s25
	v_mov_b32_e32 v14, s26
	v_mov_b32_e32 v15, s27
	global_store_dword v[18:19], v9, off offset:3072
	v_lshl_add_u64 v[18:19], v[18:19], 0, s[44:45]
	v_max_f32_e32 v10, v8, v8
	v_sub_f32_e32 v11, v15, v12
	v_max_f32_e32 v14, v14, v14
	v_max_f32_e32 v11, v14, v11
	v_max_f32_e32 v10, v11, v10
	v_sub_f32_e32 v8, v8, v10
	v_sub_f32_e32 v11, v11, v10
	v_mul_f32_e32 v8, 0x3fb8aa3b, v8
	v_mul_f32_e32 v11, 0x3fb8aa3b, v11
	v_exp_f32_e32 v8, v8
	v_exp_f32_e32 v11, v11
	v_pk_add_f32 v[12:13], v[12:13], v[12:13] op_sel:[0,1] op_sel_hi:[1,0]
	v_mul_f32_e32 v11, v123, v11
	v_mul_f32_e32 v13, v9, v8
	v_pk_add_f32 v[8:9], v[12:13], v[10:11]
	v_readlane_b32 s24, v164, 25
	v_readlane_b32 s25, v165, 25
	v_readlane_b32 s26, v166, 25
	v_readlane_b32 s27, v167, 25
	v_mov_b32_e32 v12, s20
	v_mov_b32_e32 v13, s21
	v_mov_b32_e32 v14, s22
	v_mov_b32_e32 v15, s23
	global_store_dword v[18:19], v9, off
	v_max_f32_e32 v10, v8, v8
	v_sub_f32_e32 v11, v15, v12
	v_max_f32_e32 v14, v14, v14
	v_max_f32_e32 v11, v14, v11
	v_max_f32_e32 v10, v11, v10
	v_sub_f32_e32 v8, v8, v10
	v_sub_f32_e32 v11, v11, v10
	v_mul_f32_e32 v8, 0x3fb8aa3b, v8
	v_mul_f32_e32 v11, 0x3fb8aa3b, v11
	v_exp_f32_e32 v8, v8
	v_exp_f32_e32 v11, v11
	v_pk_add_f32 v[12:13], v[12:13], v[12:13] op_sel:[0,1] op_sel_hi:[1,0]
	v_mul_f32_e32 v11, v124, v11
	v_mul_f32_e32 v13, v9, v8
	v_pk_add_f32 v[8:9], v[12:13], v[10:11]
	v_readlane_b32 s20, v164, 26
	v_readlane_b32 s21, v165, 26
	v_readlane_b32 s22, v166, 26
	v_readlane_b32 s23, v167, 26
	v_mov_b32_e32 v12, s24
	v_mov_b32_e32 v13, s25
	v_mov_b32_e32 v14, s26
	v_mov_b32_e32 v15, s27
	global_store_dword v[18:19], v9, off offset:1024
	v_max_f32_e32 v10, v8, v8
	v_sub_f32_e32 v11, v15, v12
	v_max_f32_e32 v14, v14, v14
	v_max_f32_e32 v11, v14, v11
	v_max_f32_e32 v10, v11, v10
	v_sub_f32_e32 v8, v8, v10
	v_sub_f32_e32 v11, v11, v10
	v_mul_f32_e32 v8, 0x3fb8aa3b, v8
	v_mul_f32_e32 v11, 0x3fb8aa3b, v11
	v_exp_f32_e32 v8, v8
	v_exp_f32_e32 v11, v11
	v_pk_add_f32 v[12:13], v[12:13], v[12:13] op_sel:[0,1] op_sel_hi:[1,0]
	v_mul_f32_e32 v11, v125, v11
	v_mul_f32_e32 v13, v9, v8
	v_pk_add_f32 v[8:9], v[12:13], v[10:11]
	v_readlane_b32 s24, v164, 27
	v_readlane_b32 s25, v165, 27
	v_readlane_b32 s26, v166, 27
	v_readlane_b32 s27, v167, 27
	v_mov_b32_e32 v12, s20
	v_mov_b32_e32 v13, s21
	v_mov_b32_e32 v14, s22
	v_mov_b32_e32 v15, s23
	global_store_dword v[18:19], v9, off offset:2048
	v_max_f32_e32 v10, v8, v8
	v_sub_f32_e32 v11, v15, v12
	v_max_f32_e32 v14, v14, v14
	v_max_f32_e32 v11, v14, v11
	v_max_f32_e32 v10, v11, v10
	v_sub_f32_e32 v8, v8, v10
	v_sub_f32_e32 v11, v11, v10
	v_mul_f32_e32 v8, 0x3fb8aa3b, v8
	v_mul_f32_e32 v11, 0x3fb8aa3b, v11
	v_exp_f32_e32 v8, v8
	v_exp_f32_e32 v11, v11
	v_pk_add_f32 v[12:13], v[12:13], v[12:13] op_sel:[0,1] op_sel_hi:[1,0]
	v_mul_f32_e32 v11, v126, v11
	v_mul_f32_e32 v13, v9, v8
	v_pk_add_f32 v[8:9], v[12:13], v[10:11]
	v_readlane_b32 s20, v164, 28
	v_readlane_b32 s21, v165, 28
	v_readlane_b32 s22, v166, 28
	v_readlane_b32 s23, v167, 28
	v_mov_b32_e32 v12, s24
	v_mov_b32_e32 v13, s25
	v_mov_b32_e32 v14, s26
	v_mov_b32_e32 v15, s27
	global_store_dword v[18:19], v9, off offset:3072
	v_lshl_add_u64 v[18:19], v[18:19], 0, s[44:45]
	v_max_f32_e32 v10, v8, v8
	v_sub_f32_e32 v11, v15, v12
	v_max_f32_e32 v14, v14, v14
	v_max_f32_e32 v11, v14, v11
	v_max_f32_e32 v10, v11, v10
	v_sub_f32_e32 v8, v8, v10
	v_sub_f32_e32 v11, v11, v10
	v_mul_f32_e32 v8, 0x3fb8aa3b, v8
	v_mul_f32_e32 v11, 0x3fb8aa3b, v11
	v_exp_f32_e32 v8, v8
	v_exp_f32_e32 v11, v11
	v_pk_add_f32 v[12:13], v[12:13], v[12:13] op_sel:[0,1] op_sel_hi:[1,0]
	v_mul_f32_e32 v11, v127, v11
	v_mul_f32_e32 v13, v9, v8
	v_pk_add_f32 v[8:9], v[12:13], v[10:11]
	v_readlane_b32 s24, v164, 29
	v_readlane_b32 s25, v165, 29
	v_readlane_b32 s26, v166, 29
	v_readlane_b32 s27, v167, 29
	v_mov_b32_e32 v12, s20
	v_mov_b32_e32 v13, s21
	v_mov_b32_e32 v14, s22
	v_mov_b32_e32 v15, s23
	global_store_dword v[18:19], v9, off
	v_max_f32_e32 v10, v8, v8
	v_sub_f32_e32 v11, v15, v12
	v_max_f32_e32 v14, v14, v14
	v_max_f32_e32 v11, v14, v11
	v_max_f32_e32 v10, v11, v10
	v_sub_f32_e32 v8, v8, v10
	v_sub_f32_e32 v11, v11, v10
	v_mul_f32_e32 v8, 0x3fb8aa3b, v8
	v_mul_f32_e32 v11, 0x3fb8aa3b, v11
	v_exp_f32_e32 v8, v8
	v_exp_f32_e32 v11, v11
	v_pk_add_f32 v[12:13], v[12:13], v[12:13] op_sel:[0,1] op_sel_hi:[1,0]
	v_mul_f32_e32 v11, v128, v11
	v_mul_f32_e32 v13, v9, v8
	v_pk_add_f32 v[8:9], v[12:13], v[10:11]
	v_readlane_b32 s20, v164, 30
	v_readlane_b32 s21, v165, 30
	v_readlane_b32 s22, v166, 30
	v_readlane_b32 s23, v167, 30
	v_mov_b32_e32 v12, s24
	v_mov_b32_e32 v13, s25
	v_mov_b32_e32 v14, s26
	v_mov_b32_e32 v15, s27
	global_store_dword v[18:19], v9, off offset:1024
	v_max_f32_e32 v10, v8, v8
	v_sub_f32_e32 v11, v15, v12
	v_max_f32_e32 v14, v14, v14
	v_max_f32_e32 v11, v14, v11
	v_max_f32_e32 v10, v11, v10
	v_sub_f32_e32 v8, v8, v10
	v_sub_f32_e32 v11, v11, v10
; __device__ __forceinline__ float fexpf(float x) { return __builtin_amdgcn_exp2f(1.4426950408889634f * x); }
; __device__ __forceinline__ void scan_phase(unsigned char* ws, int T0, int TS, bf16* dummy_out = nullptr) {
;     ...
;         for (int p = 0; p < NPAIR; ++p) { const float x = np[p * 256]; np[p * 256] = n;
;             const float blA = mls[MLS_CHB + head * NCH + 2 * p], blB = mls[MLS_CHB + head * NCH + 2 * p + 1];
;             const float pmP = fmaxf(mls[MLS_CHP + head * NCH + 2 * p], mls[MLS_CHP + head * NCH + 2 * p + 1] - blA), m63 = fmaxf(pmP, mrun);
;             n = fexpf(mrun - m63) * n + fexpf(pmP - m63) * x; mrun = (blA + blB) + m63; }
	v_mul_f32_e32 v8, 0x3fb8aa3b, v8
	v_mul_f32_e32 v11, 0x3fb8aa3b, v11
	v_exp_f32_e32 v8, v8
	v_exp_f32_e32 v11, v11
	v_pk_add_f32 v[12:13], v[12:13], v[12:13] op_sel:[0,1] op_sel_hi:[1,0]
	v_mul_f32_e32 v11, v129, v11
	v_mul_f32_e32 v13, v9, v8
	v_pk_add_f32 v[8:9], v[12:13], v[10:11]
	v_readlane_b32 s24, v164, 31
	v_readlane_b32 s25, v165, 31
	v_readlane_b32 s26, v166, 31
	v_readlane_b32 s27, v167, 31
	v_mov_b32_e32 v12, s20
	v_mov_b32_e32 v13, s21
	v_mov_b32_e32 v14, s22
	v_mov_b32_e32 v15, s23
	global_store_dword v[18:19], v9, off offset:2048
	v_max_f32_e32 v10, v8, v8
	v_sub_f32_e32 v11, v15, v12
	v_max_f32_e32 v14, v14, v14
	v_max_f32_e32 v11, v14, v11
	v_max_f32_e32 v10, v11, v10
	v_sub_f32_e32 v8, v8, v10
	v_sub_f32_e32 v11, v11, v10
	v_mul_f32_e32 v8, 0x3fb8aa3b, v8
	v_mul_f32_e32 v11, 0x3fb8aa3b, v11
	v_exp_f32_e32 v8, v8
	v_exp_f32_e32 v11, v11
	v_pk_add_f32 v[12:13], v[12:13], v[12:13] op_sel:[0,1] op_sel_hi:[1,0]
	v_mul_f32_e32 v11, v130, v11
	v_mul_f32_e32 v13, v9, v8
	v_pk_add_f32 v[8:9], v[12:13], v[10:11]
	v_readlane_b32 s20, v164, 32
	v_readlane_b32 s21, v165, 32
	v_readlane_b32 s22, v166, 32
	v_readlane_b32 s23, v167, 32
	v_mov_b32_e32 v12, s24
	v_mov_b32_e32 v13, s25
	v_mov_b32_e32 v14, s26
	v_mov_b32_e32 v15, s27
	global_store_dword v[18:19], v9, off offset:3072
	v_lshl_add_u64 v[18:19], v[18:19], 0, s[44:45]
	v_max_f32_e32 v10, v8, v8
	v_sub_f32_e32 v11, v15, v12
	v_max_f32_e32 v14, v14, v14
	v_max_f32_e32 v11, v14, v11
	v_max_f32_e32 v10, v11, v10
	v_sub_f32_e32 v8, v8, v10
	v_sub_f32_e32 v11, v11, v10
	v_mul_f32_e32 v8, 0x3fb8aa3b, v8
	v_mul_f32_e32 v11, 0x3fb8aa3b, v11
	v_exp_f32_e32 v8, v8
	v_exp_f32_e32 v11, v11
	v_pk_add_f32 v[12:13], v[12:13], v[12:13] op_sel:[0,1] op_sel_hi:[1,0]
	v_mul_f32_e32 v11, v131, v11
	v_mul_f32_e32 v13, v9, v8
	v_pk_add_f32 v[8:9], v[12:13], v[10:11]
	v_readlane_b32 s24, v164, 33
	v_readlane_b32 s25, v165, 33
	v_readlane_b32 s26, v166, 33
	v_readlane_b32 s27, v167, 33
	v_mov_b32_e32 v12, s20
	v_mov_b32_e32 v13, s21
	v_mov_b32_e32 v14, s22
	v_mov_b32_e32 v15, s23
	global_store_dword v[18:19], v9, off
	v_max_f32_e32 v10, v8, v8
	v_sub_f32_e32 v11, v15, v12
	v_max_f32_e32 v14, v14, v14
	v_max_f32_e32 v11, v14, v11
	v_max_f32_e32 v10, v11, v10
	v_sub_f32_e32 v8, v8, v10
	v_sub_f32_e32 v11, v11, v10
	v_mul_f32_e32 v8, 0x3fb8aa3b, v8
	v_mul_f32_e32 v11, 0x3fb8aa3b, v11
	v_exp_f32_e32 v8, v8
	v_exp_f32_e32 v11, v11
	v_pk_add_f32 v[12:13], v[12:13], v[12:13] op_sel:[0,1] op_sel_hi:[1,0]
	v_mul_f32_e32 v11, v132, v11
	v_mul_f32_e32 v13, v9, v8
	v_pk_add_f32 v[8:9], v[12:13], v[10:11]
	v_readlane_b32 s20, v164, 34
	v_readlane_b32 s21, v165, 34
	v_readlane_b32 s22, v166, 34
	v_readlane_b32 s23, v167, 34
	v_mov_b32_e32 v12, s24
	v_mov_b32_e32 v13, s25
	v_mov_b32_e32 v14, s26
	v_mov_b32_e32 v15, s27
	global_store_dword v[18:19], v9, off offset:1024
	v_max_f32_e32 v10, v8, v8
	v_sub_f32_e32 v11, v15, v12
	v_max_f32_e32 v14, v14, v14
	v_max_f32_e32 v11, v14, v11
	v_max_f32_e32 v10, v11, v10
	v_sub_f32_e32 v8, v8, v10
	v_sub_f32_e32 v11, v11, v10
	v_mul_f32_e32 v8, 0x3fb8aa3b, v8
	v_mul_f32_e32 v11, 0x3fb8aa3b, v11
	v_exp_f32_e32 v8, v8
	v_exp_f32_e32 v11, v11
	v_pk_add_f32 v[12:13], v[12:13], v[12:13] op_sel:[0,1] op_sel_hi:[1,0]
	v_mul_f32_e32 v11, v133, v11
	v_mul_f32_e32 v13, v9, v8
	v_pk_add_f32 v[8:9], v[12:13], v[10:11]
	v_readlane_b32 s24, v164, 35
	v_readlane_b32 s25, v165, 35
	v_readlane_b32 s26, v166, 35
	v_readlane_b32 s27, v167, 35
	v_mov_b32_e32 v12, s20
	v_mov_b32_e32 v13, s21
	v_mov_b32_e32 v14, s22
	v_mov_b32_e32 v15, s23
	global_store_dword v[18:19], v9, off offset:2048
	v_max_f32_e32 v10, v8, v8
	v_sub_f32_e32 v11, v15, v12
	v_max_f32_e32 v14, v14, v14
	v_max_f32_e32 v11, v14, v11
	v_max_f32_e32 v10, v11, v10
	v_sub_f32_e32 v8, v8, v10
	v_sub_f32_e32 v11, v11, v10
	v_mul_f32_e32 v8, 0x3fb8aa3b, v8
	v_mul_f32_e32 v11, 0x3fb8aa3b, v11
	v_exp_f32_e32 v8, v8
	v_exp_f32_e32 v11, v11
	v_pk_add_f32 v[12:13], v[12:13], v[12:13] op_sel:[0,1] op_sel_hi:[1,0]
	v_mul_f32_e32 v11, v134, v11
	v_mul_f32_e32 v13, v9, v8
	v_pk_add_f32 v[8:9], v[12:13], v[10:11]
	v_readlane_b32 s20, v164, 36
	v_readlane_b32 s21, v165, 36
	v_readlane_b32 s22, v166, 36
	v_readlane_b32 s23, v167, 36
	v_mov_b32_e32 v12, s24
	v_mov_b32_e32 v13, s25
	v_mov_b32_e32 v14, s26
	v_mov_b32_e32 v15, s27
	global_store_dword v[18:19], v9, off offset:3072
	v_lshl_add_u64 v[18:19], v[18:19], 0, s[44:45]
	v_max_f32_e32 v10, v8, v8
	v_sub_f32_e32 v11, v15, v12
	v_max_f32_e32 v14, v14, v14
	v_max_f32_e32 v11, v14, v11
	v_max_f32_e32 v10, v11, v10
	v_sub_f32_e32 v8, v8, v10
	v_sub_f32_e32 v11, v11, v10
	v_mul_f32_e32 v8, 0x3fb8aa3b, v8
	v_mul_f32_e32 v11, 0x3fb8aa3b, v11
	v_exp_f32_e32 v8, v8
	v_exp_f32_e32 v11, v11
	v_pk_add_f32 v[12:13], v[12:13], v[12:13] op_sel:[0,1] op_sel_hi:[1,0]
	v_mul_f32_e32 v11, v135, v11
	v_mul_f32_e32 v13, v9, v8
	v_pk_add_f32 v[8:9], v[12:13], v[10:11]
	v_readlane_b32 s24, v164, 37
	v_readlane_b32 s25, v165, 37
	v_readlane_b32 s26, v166, 37
	v_readlane_b32 s27, v167, 37
	v_mov_b32_e32 v12, s20
	v_mov_b32_e32 v13, s21
	v_mov_b32_e32 v14, s22
	v_mov_b32_e32 v15, s23
	global_store_dword v[18:19], v9, off
	v_max_f32_e32 v10, v8, v8
	v_sub_f32_e32 v11, v15, v12
	v_max_f32_e32 v14, v14, v14
	v_max_f32_e32 v11, v14, v11
	v_max_f32_e32 v10, v11, v10
	v_sub_f32_e32 v8, v8, v10
	v_sub_f32_e32 v11, v11, v10
	v_mul_f32_e32 v8, 0x3fb8aa3b, v8
	v_mul_f32_e32 v11, 0x3fb8aa3b, v11
	v_exp_f32_e32 v8, v8
	v_exp_f32_e32 v11, v11
	v_pk_add_f32 v[12:13], v[12:13], v[12:13] op_sel:[0,1] op_sel_hi:[1,0]
	v_mul_f32_e32 v11, v136, v11
	v_mul_f32_e32 v13, v9, v8
	v_pk_add_f32 v[8:9], v[12:13], v[10:11]
	v_readlane_b32 s20, v164, 38
; __device__ __forceinline__ float fexpf(float x) { return __builtin_amdgcn_exp2f(1.4426950408889634f * x); }
; __device__ __forceinline__ void scan_phase(unsigned char* ws, int T0, int TS, bf16* dummy_out = nullptr) {
;     ...
;         for (int p = 0; p < NPAIR; ++p) { const float x = np[p * 256]; np[p * 256] = n;
;             const float blA = mls[MLS_CHB + head * NCH + 2 * p], blB = mls[MLS_CHB + head * NCH + 2 * p + 1];
;             const float pmP = fmaxf(mls[MLS_CHP + head * NCH + 2 * p], mls[MLS_CHP + head * NCH + 2 * p + 1] - blA), m63 = fmaxf(pmP, mrun);
;             n = fexpf(mrun - m63) * n + fexpf(pmP - m63) * x; mrun = (blA + blB) + m63; }
	v_readlane_b32 s21, v165, 38
	v_readlane_b32 s22, v166, 38
	v_readlane_b32 s23, v167, 38
	v_mov_b32_e32 v12, s24
	v_mov_b32_e32 v13, s25
	v_mov_b32_e32 v14, s26
	v_mov_b32_e32 v15, s27
	global_store_dword v[18:19], v9, off offset:1024
	v_max_f32_e32 v10, v8, v8
	v_sub_f32_e32 v11, v15, v12
	v_max_f32_e32 v14, v14, v14
	v_max_f32_e32 v11, v14, v11
	v_max_f32_e32 v10, v11, v10
	v_sub_f32_e32 v8, v8, v10
	v_sub_f32_e32 v11, v11, v10
	v_mul_f32_e32 v8, 0x3fb8aa3b, v8
	v_mul_f32_e32 v11, 0x3fb8aa3b, v11
	v_exp_f32_e32 v8, v8
	v_exp_f32_e32 v11, v11
	v_pk_add_f32 v[12:13], v[12:13], v[12:13] op_sel:[0,1] op_sel_hi:[1,0]
	v_mul_f32_e32 v11, v137, v11
	v_mul_f32_e32 v13, v9, v8
	v_pk_add_f32 v[8:9], v[12:13], v[10:11]
	v_readlane_b32 s24, v164, 39
	v_readlane_b32 s25, v165, 39
	v_readlane_b32 s26, v166, 39
	v_readlane_b32 s27, v167, 39
	v_mov_b32_e32 v12, s20
	v_mov_b32_e32 v13, s21
	v_mov_b32_e32 v14, s22
	v_mov_b32_e32 v15, s23
	global_store_dword v[18:19], v9, off offset:2048
	v_max_f32_e32 v10, v8, v8
	v_sub_f32_e32 v11, v15, v12
	v_max_f32_e32 v14, v14, v14
	v_max_f32_e32 v11, v14, v11
	v_max_f32_e32 v10, v11, v10
	v_sub_f32_e32 v8, v8, v10
	v_sub_f32_e32 v11, v11, v10
	v_mul_f32_e32 v8, 0x3fb8aa3b, v8
	v_mul_f32_e32 v11, 0x3fb8aa3b, v11
	v_exp_f32_e32 v8, v8
	v_exp_f32_e32 v11, v11
	v_pk_add_f32 v[12:13], v[12:13], v[12:13] op_sel:[0,1] op_sel_hi:[1,0]
	v_mul_f32_e32 v11, v138, v11
	v_mul_f32_e32 v13, v9, v8
	v_pk_add_f32 v[8:9], v[12:13], v[10:11]
	v_readlane_b32 s20, v164, 40
	v_readlane_b32 s21, v165, 40
	v_readlane_b32 s22, v166, 40
	v_readlane_b32 s23, v167, 40
	v_mov_b32_e32 v12, s24
	v_mov_b32_e32 v13, s25
	v_mov_b32_e32 v14, s26
	v_mov_b32_e32 v15, s27
	global_store_dword v[18:19], v9, off offset:3072
	v_lshl_add_u64 v[18:19], v[18:19], 0, s[44:45]
	v_max_f32_e32 v10, v8, v8
	v_sub_f32_e32 v11, v15, v12
	v_max_f32_e32 v14, v14, v14
	v_max_f32_e32 v11, v14, v11
	v_max_f32_e32 v10, v11, v10
	v_sub_f32_e32 v8, v8, v10
	v_sub_f32_e32 v11, v11, v10
	v_mul_f32_e32 v8, 0x3fb8aa3b, v8
	v_mul_f32_e32 v11, 0x3fb8aa3b, v11
	v_exp_f32_e32 v8, v8
	v_exp_f32_e32 v11, v11
	v_pk_add_f32 v[12:13], v[12:13], v[12:13] op_sel:[0,1] op_sel_hi:[1,0]
	v_mul_f32_e32 v11, v139, v11
	v_mul_f32_e32 v13, v9, v8
	v_pk_add_f32 v[8:9], v[12:13], v[10:11]
	v_readlane_b32 s24, v164, 41
	v_readlane_b32 s25, v165, 41
	v_readlane_b32 s26, v166, 41
	v_readlane_b32 s27, v167, 41
	v_mov_b32_e32 v12, s20
	v_mov_b32_e32 v13, s21
	v_mov_b32_e32 v14, s22
	v_mov_b32_e32 v15, s23
	global_store_dword v[18:19], v9, off
	v_max_f32_e32 v10, v8, v8
	v_sub_f32_e32 v11, v15, v12
	v_max_f32_e32 v14, v14, v14
	v_max_f32_e32 v11, v14, v11
	v_max_f32_e32 v10, v11, v10
	v_sub_f32_e32 v8, v8, v10
	v_sub_f32_e32 v11, v11, v10
	v_mul_f32_e32 v8, 0x3fb8aa3b, v8
	v_mul_f32_e32 v11, 0x3fb8aa3b, v11
	v_exp_f32_e32 v8, v8
	v_exp_f32_e32 v11, v11
	v_pk_add_f32 v[12:13], v[12:13], v[12:13] op_sel:[0,1] op_sel_hi:[1,0]
	v_mul_f32_e32 v11, v140, v11
	v_mul_f32_e32 v13, v9, v8
	v_pk_add_f32 v[8:9], v[12:13], v[10:11]
	v_readlane_b32 s20, v164, 42
	v_readlane_b32 s21, v165, 42
	v_readlane_b32 s22, v166, 42
	v_readlane_b32 s23, v167, 42
	v_mov_b32_e32 v12, s24
	v_mov_b32_e32 v13, s25
	v_mov_b32_e32 v14, s26
	v_mov_b32_e32 v15, s27
	global_store_dword v[18:19], v9, off offset:1024
	v_max_f32_e32 v10, v8, v8
	v_sub_f32_e32 v11, v15, v12
	v_max_f32_e32 v14, v14, v14
	v_max_f32_e32 v11, v14, v11
	v_max_f32_e32 v10, v11, v10
	v_sub_f32_e32 v8, v8, v10
	v_sub_f32_e32 v11, v11, v10
	v_mul_f32_e32 v8, 0x3fb8aa3b, v8
	v_mul_f32_e32 v11, 0x3fb8aa3b, v11
	v_exp_f32_e32 v8, v8
	v_exp_f32_e32 v11, v11
	v_pk_add_f32 v[12:13], v[12:13], v[12:13] op_sel:[0,1] op_sel_hi:[1,0]
	v_mul_f32_e32 v11, v141, v11
	v_mul_f32_e32 v13, v9, v8
	v_pk_add_f32 v[8:9], v[12:13], v[10:11]
	v_readlane_b32 s24, v164, 43
	v_readlane_b32 s25, v165, 43
	v_readlane_b32 s26, v166, 43
	v_readlane_b32 s27, v167, 43
	v_mov_b32_e32 v12, s20
	v_mov_b32_e32 v13, s21
	v_mov_b32_e32 v14, s22
	v_mov_b32_e32 v15, s23
	global_store_dword v[18:19], v9, off offset:2048
	v_max_f32_e32 v10, v8, v8
	v_sub_f32_e32 v11, v15, v12
	v_max_f32_e32 v14, v14, v14
	v_max_f32_e32 v11, v14, v11
	v_max_f32_e32 v10, v11, v10
	v_sub_f32_e32 v8, v8, v10
	v_sub_f32_e32 v11, v11, v10
	v_mul_f32_e32 v8, 0x3fb8aa3b, v8
	v_mul_f32_e32 v11, 0x3fb8aa3b, v11
	v_exp_f32_e32 v8, v8
	v_exp_f32_e32 v11, v11
	v_pk_add_f32 v[12:13], v[12:13], v[12:13] op_sel:[0,1] op_sel_hi:[1,0]
	v_mul_f32_e32 v11, v142, v11
	v_mul_f32_e32 v13, v9, v8
	v_pk_add_f32 v[8:9], v[12:13], v[10:11]
	v_readlane_b32 s20, v164, 44
	v_readlane_b32 s21, v165, 44
	v_readlane_b32 s22, v166, 44
	v_readlane_b32 s23, v167, 44
	v_mov_b32_e32 v12, s24
	v_mov_b32_e32 v13, s25
	v_mov_b32_e32 v14, s26
	v_mov_b32_e32 v15, s27
	global_store_dword v[18:19], v9, off offset:3072
	v_lshl_add_u64 v[18:19], v[18:19], 0, s[44:45]
	v_max_f32_e32 v10, v8, v8
	v_sub_f32_e32 v11, v15, v12
	v_max_f32_e32 v14, v14, v14
	v_max_f32_e32 v11, v14, v11
	v_max_f32_e32 v10, v11, v10
	v_sub_f32_e32 v8, v8, v10
	v_sub_f32_e32 v11, v11, v10
	v_mul_f32_e32 v8, 0x3fb8aa3b, v8
	v_mul_f32_e32 v11, 0x3fb8aa3b, v11
	v_exp_f32_e32 v8, v8
	v_exp_f32_e32 v11, v11
	v_pk_add_f32 v[12:13], v[12:13], v[12:13] op_sel:[0,1] op_sel_hi:[1,0]
	v_mul_f32_e32 v11, v143, v11
	v_mul_f32_e32 v13, v9, v8
	v_pk_add_f32 v[8:9], v[12:13], v[10:11]
	v_readlane_b32 s24, v164, 45
	v_readlane_b32 s25, v165, 45
	v_readlane_b32 s26, v166, 45
	v_readlane_b32 s27, v167, 45
	v_mov_b32_e32 v12, s20
	v_mov_b32_e32 v13, s21
	v_mov_b32_e32 v14, s22
	v_mov_b32_e32 v15, s23
	global_store_dword v[18:19], v9, off
	v_max_f32_e32 v10, v8, v8
	v_sub_f32_e32 v11, v15, v12
	v_max_f32_e32 v14, v14, v14
; __device__ __forceinline__ float fexpf(float x) { return __builtin_amdgcn_exp2f(1.4426950408889634f * x); }
; __device__ __forceinline__ void scan_phase(unsigned char* ws, int T0, int TS, bf16* dummy_out = nullptr) {
;     ...
;         for (int p = 0; p < NPAIR; ++p) { const float x = np[p * 256]; np[p * 256] = n;
;             const float blA = mls[MLS_CHB + head * NCH + 2 * p], blB = mls[MLS_CHB + head * NCH + 2 * p + 1];
;             const float pmP = fmaxf(mls[MLS_CHP + head * NCH + 2 * p], mls[MLS_CHP + head * NCH + 2 * p + 1] - blA), m63 = fmaxf(pmP, mrun);
;             n = fexpf(mrun - m63) * n + fexpf(pmP - m63) * x; mrun = (blA + blB) + m63; }
	v_max_f32_e32 v11, v14, v11
	v_max_f32_e32 v10, v11, v10
	v_sub_f32_e32 v8, v8, v10
	v_sub_f32_e32 v11, v11, v10
	v_mul_f32_e32 v8, 0x3fb8aa3b, v8
	v_mul_f32_e32 v11, 0x3fb8aa3b, v11
	v_exp_f32_e32 v8, v8
	v_exp_f32_e32 v11, v11
	v_pk_add_f32 v[12:13], v[12:13], v[12:13] op_sel:[0,1] op_sel_hi:[1,0]
	v_mul_f32_e32 v11, v144, v11
	v_mul_f32_e32 v13, v9, v8
	v_pk_add_f32 v[8:9], v[12:13], v[10:11]
	v_readlane_b32 s20, v164, 46
	v_readlane_b32 s21, v165, 46
	v_readlane_b32 s22, v166, 46
	v_readlane_b32 s23, v167, 46
	v_mov_b32_e32 v12, s24
	v_mov_b32_e32 v13, s25
	v_mov_b32_e32 v14, s26
	v_mov_b32_e32 v15, s27
	global_store_dword v[18:19], v9, off offset:1024
	v_max_f32_e32 v10, v8, v8
	v_sub_f32_e32 v11, v15, v12
	v_max_f32_e32 v14, v14, v14
	v_max_f32_e32 v11, v14, v11
	v_max_f32_e32 v10, v11, v10
	v_sub_f32_e32 v8, v8, v10
	v_sub_f32_e32 v11, v11, v10
	v_mul_f32_e32 v8, 0x3fb8aa3b, v8
	v_mul_f32_e32 v11, 0x3fb8aa3b, v11
	v_exp_f32_e32 v8, v8
	v_exp_f32_e32 v11, v11
	v_pk_add_f32 v[12:13], v[12:13], v[12:13] op_sel:[0,1] op_sel_hi:[1,0]
	v_mul_f32_e32 v11, v145, v11
	v_mul_f32_e32 v13, v9, v8
	v_pk_add_f32 v[8:9], v[12:13], v[10:11]
	v_readlane_b32 s24, v164, 47
	v_readlane_b32 s25, v165, 47
	v_readlane_b32 s26, v166, 47
	v_readlane_b32 s27, v167, 47
	v_mov_b32_e32 v12, s20
	v_mov_b32_e32 v13, s21
	v_mov_b32_e32 v14, s22
	v_mov_b32_e32 v15, s23
	global_store_dword v[18:19], v9, off offset:2048
	v_max_f32_e32 v10, v8, v8
	v_sub_f32_e32 v11, v15, v12
	v_max_f32_e32 v14, v14, v14
	v_max_f32_e32 v11, v14, v11
	v_max_f32_e32 v10, v11, v10
	v_sub_f32_e32 v8, v8, v10
	v_sub_f32_e32 v11, v11, v10
	v_mul_f32_e32 v8, 0x3fb8aa3b, v8
	v_mul_f32_e32 v11, 0x3fb8aa3b, v11
	v_exp_f32_e32 v8, v8
	v_exp_f32_e32 v11, v11
	v_pk_add_f32 v[12:13], v[12:13], v[12:13] op_sel:[0,1] op_sel_hi:[1,0]
	v_mul_f32_e32 v11, v146, v11
	v_mul_f32_e32 v13, v9, v8
	v_pk_add_f32 v[8:9], v[12:13], v[10:11]
	v_readlane_b32 s20, v164, 48
	v_readlane_b32 s21, v165, 48
	v_readlane_b32 s22, v166, 48
	v_readlane_b32 s23, v167, 48
	v_mov_b32_e32 v12, s24
	v_mov_b32_e32 v13, s25
	v_mov_b32_e32 v14, s26
	v_mov_b32_e32 v15, s27
	global_store_dword v[18:19], v9, off offset:3072
	v_lshl_add_u64 v[18:19], v[18:19], 0, s[44:45]
	v_max_f32_e32 v10, v8, v8
	v_sub_f32_e32 v11, v15, v12
	v_max_f32_e32 v14, v14, v14
	v_max_f32_e32 v11, v14, v11
	v_max_f32_e32 v10, v11, v10
	v_sub_f32_e32 v8, v8, v10
	v_sub_f32_e32 v11, v11, v10
	v_mul_f32_e32 v8, 0x3fb8aa3b, v8
	v_mul_f32_e32 v11, 0x3fb8aa3b, v11
	v_exp_f32_e32 v8, v8
	v_exp_f32_e32 v11, v11
	v_pk_add_f32 v[12:13], v[12:13], v[12:13] op_sel:[0,1] op_sel_hi:[1,0]
	v_mul_f32_e32 v11, v147, v11
	v_mul_f32_e32 v13, v9, v8
	v_pk_add_f32 v[8:9], v[12:13], v[10:11]
	v_readlane_b32 s24, v164, 49
	v_readlane_b32 s25, v165, 49
	v_readlane_b32 s26, v166, 49
	v_readlane_b32 s27, v167, 49
	v_mov_b32_e32 v12, s20
	v_mov_b32_e32 v13, s21
	v_mov_b32_e32 v14, s22
	v_mov_b32_e32 v15, s23
	global_store_dword v[18:19], v9, off
	v_max_f32_e32 v10, v8, v8
	v_sub_f32_e32 v11, v15, v12
	v_max_f32_e32 v14, v14, v14
	v_max_f32_e32 v11, v14, v11
	v_max_f32_e32 v10, v11, v10
	v_sub_f32_e32 v8, v8, v10
	v_sub_f32_e32 v11, v11, v10
	v_mul_f32_e32 v8, 0x3fb8aa3b, v8
	v_mul_f32_e32 v11, 0x3fb8aa3b, v11
	v_exp_f32_e32 v8, v8
	v_exp_f32_e32 v11, v11
	v_pk_add_f32 v[12:13], v[12:13], v[12:13] op_sel:[0,1] op_sel_hi:[1,0]
	v_mul_f32_e32 v11, v148, v11
	v_mul_f32_e32 v13, v9, v8
	v_pk_add_f32 v[8:9], v[12:13], v[10:11]
	v_readlane_b32 s20, v164, 50
	v_readlane_b32 s21, v165, 50
	v_readlane_b32 s22, v166, 50
	v_readlane_b32 s23, v167, 50
	v_mov_b32_e32 v12, s24
	v_mov_b32_e32 v13, s25
	v_mov_b32_e32 v14, s26
	v_mov_b32_e32 v15, s27
	global_store_dword v[18:19], v9, off offset:1024
	v_max_f32_e32 v10, v8, v8
	v_sub_f32_e32 v11, v15, v12
	v_max_f32_e32 v14, v14, v14
	v_max_f32_e32 v11, v14, v11
	v_max_f32_e32 v10, v11, v10
	v_sub_f32_e32 v8, v8, v10
	v_sub_f32_e32 v11, v11, v10
	v_mul_f32_e32 v8, 0x3fb8aa3b, v8
	v_mul_f32_e32 v11, 0x3fb8aa3b, v11
	v_exp_f32_e32 v8, v8
	v_exp_f32_e32 v11, v11
	v_pk_add_f32 v[12:13], v[12:13], v[12:13] op_sel:[0,1] op_sel_hi:[1,0]
	v_mul_f32_e32 v11, v149, v11
	v_mul_f32_e32 v13, v9, v8
	v_pk_add_f32 v[8:9], v[12:13], v[10:11]
	v_readlane_b32 s24, v164, 51
	v_readlane_b32 s25, v165, 51
	v_readlane_b32 s26, v166, 51
	v_readlane_b32 s27, v167, 51
	v_mov_b32_e32 v12, s20
	v_mov_b32_e32 v13, s21
	v_mov_b32_e32 v14, s22
	v_mov_b32_e32 v15, s23
	global_store_dword v[18:19], v9, off offset:2048
	v_max_f32_e32 v10, v8, v8
	v_sub_f32_e32 v11, v15, v12
	v_max_f32_e32 v14, v14, v14
	v_max_f32_e32 v11, v14, v11
	v_max_f32_e32 v10, v11, v10
	v_sub_f32_e32 v8, v8, v10
	v_sub_f32_e32 v11, v11, v10
	v_mul_f32_e32 v8, 0x3fb8aa3b, v8
	v_mul_f32_e32 v11, 0x3fb8aa3b, v11
	v_exp_f32_e32 v8, v8
	v_exp_f32_e32 v11, v11
	v_pk_add_f32 v[12:13], v[12:13], v[12:13] op_sel:[0,1] op_sel_hi:[1,0]
	v_mul_f32_e32 v11, v150, v11
	v_mul_f32_e32 v13, v9, v8
	v_pk_add_f32 v[8:9], v[12:13], v[10:11]
	v_readlane_b32 s20, v164, 52
	v_readlane_b32 s21, v165, 52
	v_readlane_b32 s22, v166, 52
	v_readlane_b32 s23, v167, 52
	v_mov_b32_e32 v12, s24
	v_mov_b32_e32 v13, s25
	v_mov_b32_e32 v14, s26
	v_mov_b32_e32 v15, s27
	global_store_dword v[18:19], v9, off offset:3072
	v_lshl_add_u64 v[18:19], v[18:19], 0, s[44:45]
	v_max_f32_e32 v10, v8, v8
	v_sub_f32_e32 v11, v15, v12
	v_max_f32_e32 v14, v14, v14
	v_max_f32_e32 v11, v14, v11
	v_max_f32_e32 v10, v11, v10
	v_sub_f32_e32 v8, v8, v10
	v_sub_f32_e32 v11, v11, v10
	v_mul_f32_e32 v8, 0x3fb8aa3b, v8
	v_mul_f32_e32 v11, 0x3fb8aa3b, v11
	v_exp_f32_e32 v8, v8
	v_exp_f32_e32 v11, v11
	v_pk_add_f32 v[12:13], v[12:13], v[12:13] op_sel:[0,1] op_sel_hi:[1,0]
; __device__ __forceinline__ float fexpf(float x) { return __builtin_amdgcn_exp2f(1.4426950408889634f * x); }
; __device__ __forceinline__ void scan_phase(unsigned char* ws, int T0, int TS, bf16* dummy_out = nullptr) {
;     ...
;         for (int p = 0; p < NPAIR; ++p) { const float x = np[p * 256]; np[p * 256] = n;
;             const float blA = mls[MLS_CHB + head * NCH + 2 * p], blB = mls[MLS_CHB + head * NCH + 2 * p + 1];
;             const float pmP = fmaxf(mls[MLS_CHP + head * NCH + 2 * p], mls[MLS_CHP + head * NCH + 2 * p + 1] - blA), m63 = fmaxf(pmP, mrun);
;             n = fexpf(mrun - m63) * n + fexpf(pmP - m63) * x; mrun = (blA + blB) + m63; }
	v_mul_f32_e32 v11, v151, v11
	v_mul_f32_e32 v13, v9, v8
	v_pk_add_f32 v[8:9], v[12:13], v[10:11]
	v_readlane_b32 s24, v164, 53
	v_readlane_b32 s25, v165, 53
	v_readlane_b32 s26, v166, 53
	v_readlane_b32 s27, v167, 53
	v_mov_b32_e32 v12, s20
	v_mov_b32_e32 v13, s21
	v_mov_b32_e32 v14, s22
	v_mov_b32_e32 v15, s23
	global_store_dword v[18:19], v9, off
	v_max_f32_e32 v10, v8, v8
	v_sub_f32_e32 v11, v15, v12
	v_max_f32_e32 v14, v14, v14
	v_max_f32_e32 v11, v14, v11
	v_max_f32_e32 v10, v11, v10
	v_sub_f32_e32 v8, v8, v10
	v_sub_f32_e32 v11, v11, v10
	v_mul_f32_e32 v8, 0x3fb8aa3b, v8
	v_mul_f32_e32 v11, 0x3fb8aa3b, v11
	v_exp_f32_e32 v8, v8
	v_exp_f32_e32 v11, v11
	v_pk_add_f32 v[12:13], v[12:13], v[12:13] op_sel:[0,1] op_sel_hi:[1,0]
	v_mul_f32_e32 v11, v152, v11
	v_mul_f32_e32 v13, v9, v8
	v_pk_add_f32 v[8:9], v[12:13], v[10:11]
	v_readlane_b32 s20, v164, 54
	v_readlane_b32 s21, v165, 54
	v_readlane_b32 s22, v166, 54
	v_readlane_b32 s23, v167, 54
	v_mov_b32_e32 v12, s24
	v_mov_b32_e32 v13, s25
	v_mov_b32_e32 v14, s26
	v_mov_b32_e32 v15, s27
	global_store_dword v[18:19], v9, off offset:1024
	v_max_f32_e32 v10, v8, v8
	v_sub_f32_e32 v11, v15, v12
	v_max_f32_e32 v14, v14, v14
	v_max_f32_e32 v11, v14, v11
	v_max_f32_e32 v10, v11, v10
	v_sub_f32_e32 v8, v8, v10
	v_sub_f32_e32 v11, v11, v10
	v_mul_f32_e32 v8, 0x3fb8aa3b, v8
	v_mul_f32_e32 v11, 0x3fb8aa3b, v11
	v_exp_f32_e32 v8, v8
	v_exp_f32_e32 v11, v11
	v_pk_add_f32 v[12:13], v[12:13], v[12:13] op_sel:[0,1] op_sel_hi:[1,0]
	v_mul_f32_e32 v11, v153, v11
	v_mul_f32_e32 v13, v9, v8
	v_pk_add_f32 v[8:9], v[12:13], v[10:11]
	v_readlane_b32 s24, v164, 55
	v_readlane_b32 s25, v165, 55
	v_readlane_b32 s26, v166, 55
	v_readlane_b32 s27, v167, 55
	v_mov_b32_e32 v12, s20
	v_mov_b32_e32 v13, s21
	v_mov_b32_e32 v14, s22
	v_mov_b32_e32 v15, s23
	global_store_dword v[18:19], v9, off offset:2048
	v_max_f32_e32 v10, v8, v8
	v_sub_f32_e32 v11, v15, v12
	v_max_f32_e32 v14, v14, v14
	v_max_f32_e32 v11, v14, v11
	v_max_f32_e32 v10, v11, v10
	v_sub_f32_e32 v8, v8, v10
	v_sub_f32_e32 v11, v11, v10
	v_mul_f32_e32 v8, 0x3fb8aa3b, v8
	v_mul_f32_e32 v11, 0x3fb8aa3b, v11
	v_exp_f32_e32 v8, v8
	v_exp_f32_e32 v11, v11
	v_pk_add_f32 v[12:13], v[12:13], v[12:13] op_sel:[0,1] op_sel_hi:[1,0]
	v_mul_f32_e32 v11, v154, v11
	v_mul_f32_e32 v13, v9, v8
	v_pk_add_f32 v[8:9], v[12:13], v[10:11]
	v_readlane_b32 s20, v164, 56
	v_readlane_b32 s21, v165, 56
	v_readlane_b32 s22, v166, 56
	v_readlane_b32 s23, v167, 56
	v_mov_b32_e32 v12, s24
	v_mov_b32_e32 v13, s25
	v_mov_b32_e32 v14, s26
	v_mov_b32_e32 v15, s27
	global_store_dword v[18:19], v9, off offset:3072
	v_lshl_add_u64 v[18:19], v[18:19], 0, s[44:45]
	v_max_f32_e32 v10, v8, v8
	v_sub_f32_e32 v11, v15, v12
	v_max_f32_e32 v14, v14, v14
	v_max_f32_e32 v11, v14, v11
	v_max_f32_e32 v10, v11, v10
	v_sub_f32_e32 v8, v8, v10
	v_sub_f32_e32 v11, v11, v10
	v_mul_f32_e32 v8, 0x3fb8aa3b, v8
	v_mul_f32_e32 v11, 0x3fb8aa3b, v11
	v_exp_f32_e32 v8, v8
	v_exp_f32_e32 v11, v11
	v_pk_add_f32 v[12:13], v[12:13], v[12:13] op_sel:[0,1] op_sel_hi:[1,0]
	v_mul_f32_e32 v11, v155, v11
	v_mul_f32_e32 v13, v9, v8
	v_pk_add_f32 v[8:9], v[12:13], v[10:11]
	v_readlane_b32 s24, v164, 57
	v_readlane_b32 s25, v165, 57
	v_readlane_b32 s26, v166, 57
	v_readlane_b32 s27, v167, 57
	v_mov_b32_e32 v12, s20
	v_mov_b32_e32 v13, s21
	v_mov_b32_e32 v14, s22
	v_mov_b32_e32 v15, s23
	global_store_dword v[18:19], v9, off
	v_max_f32_e32 v10, v8, v8
	v_sub_f32_e32 v11, v15, v12
	v_max_f32_e32 v14, v14, v14
	v_max_f32_e32 v11, v14, v11
	v_max_f32_e32 v10, v11, v10
	v_sub_f32_e32 v8, v8, v10
	v_sub_f32_e32 v11, v11, v10
	v_mul_f32_e32 v8, 0x3fb8aa3b, v8
	v_mul_f32_e32 v11, 0x3fb8aa3b, v11
	v_exp_f32_e32 v8, v8
	v_exp_f32_e32 v11, v11
	v_pk_add_f32 v[12:13], v[12:13], v[12:13] op_sel:[0,1] op_sel_hi:[1,0]
	v_mul_f32_e32 v11, v156, v11
	v_mul_f32_e32 v13, v9, v8
	v_pk_add_f32 v[8:9], v[12:13], v[10:11]
	v_readlane_b32 s20, v164, 58
	v_readlane_b32 s21, v165, 58
	v_readlane_b32 s22, v166, 58
	v_readlane_b32 s23, v167, 58
	v_mov_b32_e32 v12, s24
	v_mov_b32_e32 v13, s25
	v_mov_b32_e32 v14, s26
	v_mov_b32_e32 v15, s27
	global_store_dword v[18:19], v9, off offset:1024
	v_max_f32_e32 v10, v8, v8
	v_sub_f32_e32 v11, v15, v12
	v_max_f32_e32 v14, v14, v14
	v_max_f32_e32 v11, v14, v11
	v_max_f32_e32 v10, v11, v10
	v_sub_f32_e32 v8, v8, v10
	v_sub_f32_e32 v11, v11, v10
	v_mul_f32_e32 v8, 0x3fb8aa3b, v8
	v_mul_f32_e32 v11, 0x3fb8aa3b, v11
	v_exp_f32_e32 v8, v8
	v_exp_f32_e32 v11, v11
	v_pk_add_f32 v[12:13], v[12:13], v[12:13] op_sel:[0,1] op_sel_hi:[1,0]
	v_mul_f32_e32 v11, v157, v11
	v_mul_f32_e32 v13, v9, v8
; __device__ __forceinline__ float fexpf(float x) { return __builtin_amdgcn_exp2f(1.4426950408889634f * x); }
; __device__ __forceinline__ void scan_phase(unsigned char* ws, int T0, int TS, bf16* dummy_out = nullptr) {
;     ...
;         for (int p = 0; p < NPAIR; ++p) { const float x = np[p * 256]; np[p * 256] = n;
;             const float blA = mls[MLS_CHB + head * NCH + 2 * p], blB = mls[MLS_CHB + head * NCH + 2 * p + 1];
;             const float pmP = fmaxf(mls[MLS_CHP + head * NCH + 2 * p], mls[MLS_CHP + head * NCH + 2 * p + 1] - blA), m63 = fmaxf(pmP, mrun);
;             n = fexpf(mrun - m63) * n + fexpf(pmP - m63) * x; mrun = (blA + blB) + m63; }
	v_pk_add_f32 v[8:9], v[12:13], v[10:11]
	v_readlane_b32 s24, v164, 59
	v_readlane_b32 s25, v165, 59
	v_readlane_b32 s26, v166, 59
	v_readlane_b32 s27, v167, 59
	v_mov_b32_e32 v12, s20
	v_mov_b32_e32 v13, s21
	v_mov_b32_e32 v14, s22
	v_mov_b32_e32 v15, s23
	global_store_dword v[18:19], v9, off offset:2048
	v_max_f32_e32 v10, v8, v8
	v_sub_f32_e32 v11, v15, v12
	v_max_f32_e32 v14, v14, v14
	v_max_f32_e32 v11, v14, v11
	v_max_f32_e32 v10, v11, v10
	v_sub_f32_e32 v8, v8, v10
	v_sub_f32_e32 v11, v11, v10
	v_mul_f32_e32 v8, 0x3fb8aa3b, v8
	v_mul_f32_e32 v11, 0x3fb8aa3b, v11
	v_exp_f32_e32 v8, v8
	v_exp_f32_e32 v11, v11
	v_pk_add_f32 v[12:13], v[12:13], v[12:13] op_sel:[0,1] op_sel_hi:[1,0]
	v_mul_f32_e32 v11, v158, v11
	v_mul_f32_e32 v13, v9, v8
	v_pk_add_f32 v[8:9], v[12:13], v[10:11]
	v_readlane_b32 s20, v164, 60
	v_readlane_b32 s21, v165, 60
	v_readlane_b32 s22, v166, 60
	v_readlane_b32 s23, v167, 60
	v_mov_b32_e32 v12, s24
	v_mov_b32_e32 v13, s25
	v_mov_b32_e32 v14, s26
	v_mov_b32_e32 v15, s27
	global_store_dword v[18:19], v9, off offset:3072
	v_lshl_add_u64 v[18:19], v[18:19], 0, s[44:45]
	v_max_f32_e32 v10, v8, v8
	v_sub_f32_e32 v11, v15, v12
	v_max_f32_e32 v14, v14, v14
	v_max_f32_e32 v11, v14, v11
	v_max_f32_e32 v10, v11, v10
	v_sub_f32_e32 v8, v8, v10
	v_sub_f32_e32 v11, v11, v10
	v_mul_f32_e32 v8, 0x3fb8aa3b, v8
	v_mul_f32_e32 v11, 0x3fb8aa3b, v11
	v_exp_f32_e32 v8, v8
	v_exp_f32_e32 v11, v11
	v_pk_add_f32 v[12:13], v[12:13], v[12:13] op_sel:[0,1] op_sel_hi:[1,0]
	v_mul_f32_e32 v11, v159, v11
	v_mul_f32_e32 v13, v9, v8
	v_pk_add_f32 v[8:9], v[12:13], v[10:11]
	v_readlane_b32 s24, v164, 61
	v_readlane_b32 s25, v165, 61
	v_readlane_b32 s26, v166, 61
	v_readlane_b32 s27, v167, 61
	v_mov_b32_e32 v12, s20
	v_mov_b32_e32 v13, s21
	v_mov_b32_e32 v14, s22
	v_mov_b32_e32 v15, s23
	global_store_dword v[18:19], v9, off
	v_max_f32_e32 v10, v8, v8
	v_sub_f32_e32 v11, v15, v12
	v_max_f32_e32 v14, v14, v14
	v_max_f32_e32 v11, v14, v11
	v_max_f32_e32 v10, v11, v10
	v_sub_f32_e32 v8, v8, v10
	v_sub_f32_e32 v11, v11, v10
	v_mul_f32_e32 v8, 0x3fb8aa3b, v8
	v_mul_f32_e32 v11, 0x3fb8aa3b, v11
	v_exp_f32_e32 v8, v8
	v_exp_f32_e32 v11, v11
	v_pk_add_f32 v[12:13], v[12:13], v[12:13] op_sel:[0,1] op_sel_hi:[1,0]
	v_mul_f32_e32 v11, v160, v11
	v_mul_f32_e32 v13, v9, v8
	v_pk_add_f32 v[8:9], v[12:13], v[10:11]
	v_readlane_b32 s20, v164, 62
	v_readlane_b32 s21, v165, 62
	v_readlane_b32 s22, v166, 62
	v_readlane_b32 s23, v167, 62
	v_mov_b32_e32 v12, s24
	v_mov_b32_e32 v13, s25
	v_mov_b32_e32 v14, s26
	v_mov_b32_e32 v15, s27
	global_store_dword v[18:19], v9, off offset:1024
	v_max_f32_e32 v10, v8, v8
	v_sub_f32_e32 v11, v15, v12
	v_max_f32_e32 v14, v14, v14
	v_max_f32_e32 v11, v14, v11
	v_max_f32_e32 v10, v11, v10
	v_sub_f32_e32 v8, v8, v10
	v_sub_f32_e32 v11, v11, v10
	v_mul_f32_e32 v8, 0x3fb8aa3b, v8
	v_mul_f32_e32 v11, 0x3fb8aa3b, v11
	v_exp_f32_e32 v8, v8
	v_exp_f32_e32 v11, v11
	v_pk_add_f32 v[12:13], v[12:13], v[12:13] op_sel:[0,1] op_sel_hi:[1,0]
	v_mul_f32_e32 v11, v161, v11
	v_mul_f32_e32 v13, v9, v8
	v_pk_add_f32 v[8:9], v[12:13], v[10:11]
	v_readlane_b32 s24, v164, 63
	v_readlane_b32 s25, v165, 63
	v_readlane_b32 s26, v166, 63
	v_readlane_b32 s27, v167, 63
	v_mov_b32_e32 v12, s20
	v_mov_b32_e32 v13, s21
	v_mov_b32_e32 v14, s22
	v_mov_b32_e32 v15, s23
	global_store_dword v[18:19], v9, off offset:2048
	v_max_f32_e32 v10, v8, v8
	v_sub_f32_e32 v11, v15, v12
	v_max_f32_e32 v14, v14, v14
	v_max_f32_e32 v11, v14, v11
	v_max_f32_e32 v10, v11, v10
	v_sub_f32_e32 v8, v8, v10
	v_sub_f32_e32 v11, v11, v10
	v_mul_f32_e32 v8, 0x3fb8aa3b, v8
	v_mul_f32_e32 v11, 0x3fb8aa3b, v11
	v_exp_f32_e32 v8, v8
	v_exp_f32_e32 v11, v11
	v_pk_add_f32 v[12:13], v[12:13], v[12:13] op_sel:[0,1] op_sel_hi:[1,0]
	v_mul_f32_e32 v11, v162, v11
	v_mul_f32_e32 v13, v9, v8
	v_pk_add_f32 v[8:9], v[12:13], v[10:11]
	v_mov_b32_e32 v12, s24
	v_mov_b32_e32 v13, s25
	v_mov_b32_e32 v14, s26
	v_mov_b32_e32 v15, s27
	global_store_dword v[18:19], v9, off offset:3072
	v_max_f32_e32 v10, v8, v8
	v_sub_f32_e32 v11, v15, v12
	v_max_f32_e32 v14, v14, v14
	v_max_f32_e32 v11, v14, v11
	v_max_f32_e32 v10, v11, v10
	v_sub_f32_e32 v8, v8, v10
	v_sub_f32_e32 v11, v11, v10
	v_mul_f32_e32 v8, 0x3fb8aa3b, v8
	v_mul_f32_e32 v11, 0x3fb8aa3b, v11
	v_exp_f32_e32 v8, v8
	v_exp_f32_e32 v11, v11
	v_pk_add_f32 v[12:13], v[12:13], v[12:13] op_sel:[0,1] op_sel_hi:[1,0]
	v_mul_f32_e32 v11, v163, v11
	v_mul_f32_e32 v13, v9, v8
	v_pk_add_f32 v[8:9], v[12:13], v[10:11]
	v_add_u32_e32 v85, s39, v85
	v_cmp_lt_i32_e32 vcc, s14, v85
	s_or_b64 s[6:7], vcc, s[6:7]
	s_andn2_b64 exec, exec, s[6:7]
	s_cbranch_execnz .LBB0_467
